# X-phase fillers capped at 3 per MFMA gap, decay-factor loads issued under the SA-half MFMAs
# baseline (speedup 1.0000x reference)
.Lmy_ck_nz:
	s_mov_b32 s100, 0xe000
	s_cmp_eq_u32 s23, 0
	s_cselect_b32 s100, 0x1c000, s100
	s_mov_b32 s101, 0x12e00
	s_cselect_b32 s101, 0x22100, s101
	s_lshl_b32 s96, s23, 13
	s_add_i32 s97, s96, 0x18000
	s_add_i32 s96, s96, 0xa000
	v_add_u32_e32 v225, s100, v1
	v_add_u32_e32 v236, s100, v0
	v_add_u32_e32 v34, s100, v10
	v_add_u32_e32 v226, s100, v2
	v_add_u32_e32 v227, s100, v3
	v_add_u32_e32 v228, s100, v4
	v_add_u32_e32 v229, s100, v5
	v_add_u32_e32 v237, s100, v6
	v_add_u32_e32 v238, s100, v7
	v_add_u32_e32 v230, s96, v8
	v_add_u32_e32 v239, s96, v9
	v_add_u32_e32 v231, s97, v8
	v_add_u32_e32 v26, s101, v1
	v_add_u32_e32 v27, s101, v0
	v_add_u32_e32 v35, s101, v10
	v_add_u32_e32 v28, s101, v2
	v_add_u32_e32 v29, s101, v3
	v_add_u32_e32 v30, s101, v4
	v_add_u32_e32 v31, s101, v5
	v_add_u32_e32 v32, s101, v6
	v_add_u32_e32 v33, s101, v7
	ds_read_b64 v[80:81], v237
	ds_read_b64 v[82:83], v238
	ds_read_b32 v36, v239
	ds_read_b32 v37, v239 offset:256
	ds_read_b128 v[88:91], v225
	ds_read_b128 v[92:95], v225 offset:1024
	ds_read_b128 v[96:99], v225 offset:2048
	ds_read_b128 v[100:103], v225 offset:3072
	ds_read_b32 v104, v227 offset:4
	ds_read_b32 v105, v227 offset:76
	ds_read_b64 v[106:107], v227 offset:8
	ds_read_b64 v[108:109], v227 offset:40
	ds_read_b32 v126, v229 offset:4
	ds_read_b32 v127, v229 offset:76
	ds_read_b64 v[128:129], v229 offset:8
	ds_read_b64 v[130:131], v229 offset:40
	ds_read_b64 v[110:111], v228
	ds_read_b64 v[112:113], v228 offset:32
	ds_read_b64 v[114:115], v228 offset:64
	ds_read_b64 v[116:117], v228 offset:96
	ds_read_b64 v[118:119], v228 offset:8
	ds_read_b64 v[120:121], v228 offset:40
	ds_read_b64 v[122:123], v228 offset:72
	ds_read_b64 v[124:125], v228 offset:104
	s_waitcnt lgkmcnt(15)
	v_mfma_f32_16x16x4_f32 v[240:243], v80, v36, 0
	v_mfma_f32_16x16x4_f32 v[240:243], v81, v37, v[240:243]
	v_mfma_f32_16x16x4_f32 v[240:243], v88, v208, v[240:243]
	ds_read_b64 v[186:187], v34
	ds_read_b64 v[190:191], v34 offset:1024
	v_mfma_f32_16x16x4_f32 v[244:247], v89, v209, 0
	ds_read_b64 v[194:195], v34 offset:2048
	ds_read_b64 v[198:199], v34 offset:3072
	v_mfma_f32_16x16x4_f32 v[240:243], v90, v210, v[240:243]
	ds_read_b64 v[184:185], v236
	ds_read_b64 v[188:189], v236 offset:1024
	ds_read_b64 v[132:133], v237 offset:9984
	v_mfma_f32_16x16x4_f32 v[244:247], v91, v211, v[244:247]
	ds_read_b64 v[134:135], v238 offset:9984
	ds_read_b64 v[192:193], v236 offset:2048
	ds_read_b64 v[196:197], v236 offset:3072
	v_mfma_f32_16x16x4_f32 v[240:243], v92, v212, v[240:243]
	ds_read_b32 v38, v239 offset:2048
	ds_read_b32 v39, v239 offset:2304
	ds_read_b128 v[140:143], v225 offset:9984
	v_mfma_f32_16x16x4_f32 v[244:247], v93, v213, v[244:247]
	ds_read_b128 v[144:147], v225 offset:11008
	ds_read_b128 v[148:151], v225 offset:12032
	ds_read_b128 v[152:155], v225 offset:13056
	v_mfma_f32_16x16x4_f32 v[240:243], v94, v214, v[240:243]
	ds_read_b32 v156, v227 offset:9988
	ds_read_b32 v157, v227 offset:10060
	v_mfma_f32_16x16x4_f32 v[244:247], v95, v215, v[244:247]
	ds_read_b64 v[158:159], v227 offset:9992
	ds_read_b64 v[160:161], v227 offset:10024
	v_mfma_f32_16x16x4_f32 v[240:243], v96, v216, v[240:243]
	ds_read_b32 v178, v229 offset:9988
	ds_read_b32 v179, v229 offset:10060
	v_mfma_f32_16x16x4_f32 v[244:247], v97, v217, v[244:247]
	ds_read_b64 v[180:181], v229 offset:9992
	ds_read_b64 v[182:183], v229 offset:10024
	v_mfma_f32_16x16x4_f32 v[240:243], v98, v218, v[240:243]
	ds_read_b64 v[162:163], v228 offset:9984
	ds_read_b64 v[164:165], v228 offset:10016
	v_mfma_f32_16x16x4_f32 v[244:247], v99, v219, v[244:247]
	ds_read_b64 v[166:167], v228 offset:10048
	ds_read_b64 v[168:169], v228 offset:10080
	v_mfma_f32_16x16x4_f32 v[240:243], v100, v220, v[240:243]
	ds_read_b64 v[170:171], v228 offset:9992
	ds_read_b64 v[172:173], v228 offset:10024
	v_mfma_f32_16x16x4_f32 v[244:247], v101, v221, v[244:247]
	ds_read_b64 v[174:175], v228 offset:10056
	ds_read_b64 v[176:177], v228 offset:10088
	v_mfma_f32_16x16x4_f32 v[240:243], v102, v222, v[240:243]
	v_mfma_f32_16x16x4_f32 v[244:247], v103, v223, v[244:247]
	s_waitcnt lgkmcnt(15)
	v_mfma_f32_16x16x4_f32 v[208:211], v186, v36, v[208:211]
	s_nop 2
	v_pk_add_f32 v[240:241], v[240:241], v[244:245]
	v_pk_add_f32 v[242:243], v[242:243], v[246:247]
	v_fmac_f32_e32 v241, v104, v240
	v_mfma_f32_16x16x4_f32 v[212:215], v190, v36, v[212:215]
	v_pk_fma_f32 v[242:243], v[106:107], v[240:241], v[242:243] op_sel:[0,0,0] op_sel_hi:[1,0,1]
	v_pk_fma_f32 v[242:243], v[108:109], v[240:241], v[242:243] op_sel:[0,1,0] op_sel_hi:[1,1,1]
	v_fmac_f32_e32 v243, v105, v242
	v_mfma_f32_16x16x4_f32 v[216:219], v194, v36, v[216:219]
	ds_bpermute_b32 v204, v232, v240
	ds_bpermute_b32 v205, v232, v241
	ds_bpermute_b32 v206, v232, v242
	v_mfma_f32_16x16x4_f32 v[72:75], v132, v38, 0
	ds_bpermute_b32 v207, v232, v243
	s_waitcnt lgkmcnt(2)
	v_pk_fma_f32 v[240:241], v[110:111], v[204:205], v[240:241] op_sel:[0,0,0] op_sel_hi:[1,0,1]
	v_pk_fma_f32 v[240:241], v[112:113], v[204:205], v[240:241] op_sel:[0,1,0] op_sel_hi:[1,1,1]
	v_mfma_f32_16x16x4_f32 v[72:75], v133, v39, v[72:75]
	s_waitcnt lgkmcnt(0)
	v_pk_fma_f32 v[240:241], v[114:115], v[206:207], v[240:241] op_sel:[0,0,0] op_sel_hi:[1,0,1]
	v_pk_fma_f32 v[240:241], v[116:117], v[206:207], v[240:241] op_sel:[0,1,0] op_sel_hi:[1,1,1]
	v_pk_fma_f32 v[242:243], v[118:119], v[204:205], v[242:243] op_sel:[0,0,0] op_sel_hi:[1,0,1]
	v_mfma_f32_16x16x4_f32 v[220:223], v198, v36, v[220:223]
	v_pk_fma_f32 v[242:243], v[120:121], v[204:205], v[242:243] op_sel:[0,1,0] op_sel_hi:[1,1,1]
	v_pk_fma_f32 v[242:243], v[122:123], v[206:207], v[242:243] op_sel:[0,0,0] op_sel_hi:[1,0,1]
	v_pk_fma_f32 v[242:243], v[124:125], v[206:207], v[242:243] op_sel:[0,1,0] op_sel_hi:[1,1,1]
	v_mfma_f32_16x16x4_f32 v[208:211], v187, v37, v[208:211]
	v_fmac_f32_e32 v241, v126, v240
	v_pk_fma_f32 v[242:243], v[128:129], v[240:241], v[242:243] op_sel:[0,0,0] op_sel_hi:[1,0,1]
	v_pk_fma_f32 v[242:243], v[130:131], v[240:241], v[242:243] op_sel:[0,1,0] op_sel_hi:[1,1,1]
	v_mfma_f32_16x16x4_f32 v[212:215], v191, v37, v[212:215]
	v_fmac_f32_e32 v243, v127, v242
	v_mov_b32_e32 v252, v240
	v_mov_b32_e32 v253, v241
	v_mfma_f32_16x16x4_f32 v[216:219], v195, v37, v[216:219]
	v_mov_b32_e32 v254, v242
	v_mov_b32_e32 v255, v243
	s_nop 0
	v_permlane32_swap_b32_e32 v252, v254
	v_mfma_f32_16x16x4_f32 v[220:223], v199, v37, v[220:223]
	v_permlane32_swap_b32_e32 v253, v255
	v_mfma_f32_16x16x4_f32 v[208:211], v184, v252, v[208:211]
	ds_read_b128 v[88:91], v226
	v_mfma_f32_16x16x4_f32 v[212:215], v188, v252, v[212:215]
	ds_read_b128 v[92:95], v226 offset:64
	v_mfma_f32_16x16x4_f32 v[216:219], v192, v252, v[216:219]
	ds_read_b128 v[96:99], v226 offset:128
	v_mfma_f32_16x16x4_f32 v[220:223], v196, v252, v[220:223]
	ds_read_b128 v[100:103], v226 offset:192
	v_mfma_f32_16x16x4_f32 v[208:211], v185, v253, v[208:211]
	v_mfma_f32_16x16x4_f32 v[212:215], v189, v253, v[212:215]
	v_mfma_f32_16x16x4_f32 v[216:219], v193, v253, v[216:219]
	v_mfma_f32_16x16x4_f32 v[220:223], v197, v253, v[220:223]
	v_mfma_f32_16x16x4_f32 v[248:251], v82, v252, v[240:243]
	v_mfma_f32_16x16x4_f32 v[248:251], v83, v253, v[248:251]
	s_waitcnt lgkmcnt(3)
	v_pk_mul_f32 v[208:209], v[208:209], v[88:89]
	v_pk_mul_f32 v[210:211], v[210:211], v[90:91]
	s_nop 0
	v_mfma_f32_16x16x4_f32 v[72:75], v140, v208, v[72:75]
	s_waitcnt lgkmcnt(2)
	v_pk_mul_f32 v[212:213], v[212:213], v[92:93]
	v_mfma_f32_16x16x4_f32 v[244:247], v141, v209, 0
	v_pk_mul_f32 v[214:215], v[214:215], v[94:95]
	v_mfma_f32_16x16x4_f32 v[72:75], v142, v210, v[72:75]
	s_waitcnt lgkmcnt(1)
	v_pk_mul_f32 v[216:217], v[216:217], v[96:97]
	v_mfma_f32_16x16x4_f32 v[244:247], v143, v211, v[244:247]
	v_pk_mul_f32 v[218:219], v[218:219], v[98:99]
	v_mfma_f32_16x16x4_f32 v[72:75], v144, v212, v[72:75]
	s_waitcnt lgkmcnt(0)
	v_pk_mul_f32 v[220:221], v[220:221], v[100:101]
	v_mfma_f32_16x16x4_f32 v[244:247], v145, v213, v[244:247]
	v_pk_mul_f32 v[222:223], v[222:223], v[102:103]
	v_mfma_f32_16x16x4_f32 v[72:75], v146, v214, v[72:75]
	s_mov_b64 exec, s[98:99]
	ds_write_b32 v231, v248
	ds_write_b32 v231, v249 offset:256
	ds_write_b32 v231, v250 offset:512
	ds_write_b32 v231, v251 offset:768
	s_mov_b64 exec, -1
	ds_read_b64 v[186:187], v34 offset:9984
	ds_read_b64 v[190:191], v34 offset:11008
	v_mfma_f32_16x16x4_f32 v[244:247], v147, v215, v[244:247]
	ds_read_b64 v[194:195], v34 offset:12032
	ds_read_b64 v[198:199], v34 offset:13056
	v_mfma_f32_16x16x4_f32 v[72:75], v148, v216, v[72:75]
	ds_read_b64 v[184:185], v236 offset:9984
	ds_read_b64 v[188:189], v236 offset:11008
	ds_read_b64 v[80:81], v32
	v_mfma_f32_16x16x4_f32 v[244:247], v149, v217, v[244:247]
	ds_read_b64 v[82:83], v33
	ds_read_b32 v36, v239 offset:4096
	ds_read_b64 v[192:193], v236 offset:12032
	v_mfma_f32_16x16x4_f32 v[72:75], v150, v218, v[72:75]
	ds_read_b64 v[196:197], v236 offset:13056
	ds_read_b32 v37, v239 offset:4352
	ds_read_b128 v[88:91], v26
	v_mfma_f32_16x16x4_f32 v[244:247], v151, v219, v[244:247]
	ds_read_b128 v[92:95], v26 offset:1024
	ds_read_b128 v[96:99], v26 offset:2048
	ds_read_b128 v[100:103], v26 offset:3072
	v_mfma_f32_16x16x4_f32 v[72:75], v152, v220, v[72:75]
	ds_read_b32 v104, v29 offset:4
	ds_read_b32 v105, v29 offset:76
	ds_read_b64 v[106:107], v29 offset:8
	v_mfma_f32_16x16x4_f32 v[244:247], v153, v221, v[244:247]
	ds_read_b64 v[108:109], v29 offset:40
	ds_read_b32 v126, v31 offset:4
	ds_read_b32 v127, v31 offset:76
	v_mfma_f32_16x16x4_f32 v[72:75], v154, v222, v[72:75]
	ds_read_b64 v[128:129], v31 offset:8
	ds_read_b64 v[130:131], v31 offset:40
	ds_read_b64 v[110:111], v30
	v_mfma_f32_16x16x4_f32 v[244:247], v155, v223, v[244:247]
	ds_read_b64 v[112:113], v30 offset:32
	ds_read_b64 v[114:115], v30 offset:64
	ds_read_b64 v[116:117], v30 offset:96
	ds_read_b64 v[118:119], v30 offset:8
	ds_read_b64 v[120:121], v30 offset:40
	ds_read_b64 v[122:123], v30 offset:72
	ds_read_b64 v[124:125], v30 offset:104
	s_waitcnt lgkmcnt(15)
	v_mfma_f32_16x16x4_f32 v[208:211], v186, v38, v[208:211]
	s_nop 1
	v_pk_add_f32 v[72:73], v[72:73], v[244:245]
	v_pk_add_f32 v[74:75], v[74:75], v[246:247]
	v_fmac_f32_e32 v73, v156, v72
	v_mfma_f32_16x16x4_f32 v[212:215], v190, v38, v[212:215]
	v_pk_fma_f32 v[74:75], v[158:159], v[72:73], v[74:75] op_sel:[0,0,0] op_sel_hi:[1,0,1]
	v_pk_fma_f32 v[74:75], v[160:161], v[72:73], v[74:75] op_sel:[0,1,0] op_sel_hi:[1,1,1]
	v_fmac_f32_e32 v75, v157, v74
	v_mfma_f32_16x16x4_f32 v[216:219], v194, v38, v[216:219]
	ds_bpermute_b32 v204, v232, v72
	ds_bpermute_b32 v205, v232, v73
	ds_bpermute_b32 v206, v232, v74
	v_mfma_f32_16x16x4_f32 v[240:243], v80, v36, 0
	ds_bpermute_b32 v207, v232, v75
	s_waitcnt lgkmcnt(2)
	v_pk_fma_f32 v[72:73], v[162:163], v[204:205], v[72:73] op_sel:[0,0,0] op_sel_hi:[1,0,1]
	v_pk_fma_f32 v[72:73], v[164:165], v[204:205], v[72:73] op_sel:[0,1,0] op_sel_hi:[1,1,1]
	v_mfma_f32_16x16x4_f32 v[240:243], v81, v37, v[240:243]
	s_waitcnt lgkmcnt(0)
	v_pk_fma_f32 v[72:73], v[166:167], v[206:207], v[72:73] op_sel:[0,0,0] op_sel_hi:[1,0,1]
	v_pk_fma_f32 v[72:73], v[168:169], v[206:207], v[72:73] op_sel:[0,1,0] op_sel_hi:[1,1,1]
	v_pk_fma_f32 v[74:75], v[170:171], v[204:205], v[74:75] op_sel:[0,0,0] op_sel_hi:[1,0,1]
	v_mfma_f32_16x16x4_f32 v[220:223], v198, v38, v[220:223]
	v_pk_fma_f32 v[74:75], v[172:173], v[204:205], v[74:75] op_sel:[0,1,0] op_sel_hi:[1,1,1]
	v_pk_fma_f32 v[74:75], v[174:175], v[206:207], v[74:75] op_sel:[0,0,0] op_sel_hi:[1,0,1]
	v_pk_fma_f32 v[74:75], v[176:177], v[206:207], v[74:75] op_sel:[0,1,0] op_sel_hi:[1,1,1]
	v_mfma_f32_16x16x4_f32 v[208:211], v187, v39, v[208:211]
	v_fmac_f32_e32 v73, v178, v72
	v_pk_fma_f32 v[74:75], v[180:181], v[72:73], v[74:75] op_sel:[0,0,0] op_sel_hi:[1,0,1]
	v_pk_fma_f32 v[74:75], v[182:183], v[72:73], v[74:75] op_sel:[0,1,0] op_sel_hi:[1,1,1]
	v_mfma_f32_16x16x4_f32 v[212:215], v191, v39, v[212:215]
	v_fmac_f32_e32 v75, v179, v74
	v_mov_b32_e32 v252, v72
	v_mov_b32_e32 v253, v73
	v_mfma_f32_16x16x4_f32 v[216:219], v195, v39, v[216:219]
	v_mov_b32_e32 v254, v74
	v_mov_b32_e32 v255, v75
	s_nop 0
	v_permlane32_swap_b32_e32 v252, v254
	v_mfma_f32_16x16x4_f32 v[220:223], v199, v39, v[220:223]
	v_permlane32_swap_b32_e32 v253, v255
	v_mfma_f32_16x16x4_f32 v[208:211], v184, v252, v[208:211]
	ds_read_b128 v[140:143], v226 offset:9984
	v_mfma_f32_16x16x4_f32 v[212:215], v188, v252, v[212:215]
	ds_read_b128 v[144:147], v226 offset:10048
	v_mfma_f32_16x16x4_f32 v[216:219], v192, v252, v[216:219]
	ds_read_b128 v[148:151], v226 offset:10112
	v_mfma_f32_16x16x4_f32 v[220:223], v196, v252, v[220:223]
	ds_read_b128 v[152:155], v226 offset:10176
	v_mfma_f32_16x16x4_f32 v[208:211], v185, v253, v[208:211]
	v_mfma_f32_16x16x4_f32 v[212:215], v189, v253, v[212:215]
	v_mfma_f32_16x16x4_f32 v[216:219], v193, v253, v[216:219]
	v_mfma_f32_16x16x4_f32 v[220:223], v197, v253, v[220:223]
	v_mfma_f32_16x16x4_f32 v[248:251], v134, v252, v[72:75]
	v_mfma_f32_16x16x4_f32 v[248:251], v135, v253, v[248:251]
	s_waitcnt lgkmcnt(3)
	v_pk_mul_f32 v[208:209], v[208:209], v[140:141]
	v_pk_mul_f32 v[210:211], v[210:211], v[142:143]
	s_nop 0
	v_mfma_f32_16x16x4_f32 v[240:243], v88, v208, v[240:243]
	s_waitcnt lgkmcnt(2)
	v_pk_mul_f32 v[212:213], v[212:213], v[144:145]
	v_mfma_f32_16x16x4_f32 v[244:247], v89, v209, 0
	v_pk_mul_f32 v[214:215], v[214:215], v[146:147]
	v_mfma_f32_16x16x4_f32 v[240:243], v90, v210, v[240:243]
	s_waitcnt lgkmcnt(1)
	v_pk_mul_f32 v[216:217], v[216:217], v[148:149]
	v_mfma_f32_16x16x4_f32 v[244:247], v91, v211, v[244:247]
	v_pk_mul_f32 v[218:219], v[218:219], v[150:151]
	v_mfma_f32_16x16x4_f32 v[240:243], v92, v212, v[240:243]
	s_waitcnt lgkmcnt(0)
	v_pk_mul_f32 v[220:221], v[220:221], v[152:153]
	v_mfma_f32_16x16x4_f32 v[244:247], v93, v213, v[244:247]
	v_pk_mul_f32 v[222:223], v[222:223], v[154:155]
	v_mfma_f32_16x16x4_f32 v[240:243], v94, v214, v[240:243]
	s_mov_b64 exec, s[98:99]
	ds_write_b32 v231, v248 offset:2048
	ds_write_b32 v231, v249 offset:2304
	ds_write_b32 v231, v250 offset:2560
	ds_write_b32 v231, v251 offset:2816
	s_mov_b64 exec, -1
	ds_read_b64 v[186:187], v35
	ds_read_b64 v[190:191], v35 offset:1024
	v_mfma_f32_16x16x4_f32 v[244:247], v95, v215, v[244:247]
	ds_read_b64 v[194:195], v35 offset:2048
	ds_read_b64 v[198:199], v35 offset:3072
	v_mfma_f32_16x16x4_f32 v[240:243], v96, v216, v[240:243]
	ds_read_b64 v[184:185], v27
	ds_read_b64 v[188:189], v27 offset:1024
	ds_read_b64 v[132:133], v32 offset:9984
	v_mfma_f32_16x16x4_f32 v[244:247], v97, v217, v[244:247]
	ds_read_b64 v[134:135], v33 offset:9984
	ds_read_b32 v38, v239 offset:6144
	ds_read_b64 v[192:193], v27 offset:2048
	v_mfma_f32_16x16x4_f32 v[240:243], v98, v218, v[240:243]
	ds_read_b64 v[196:197], v27 offset:3072
	ds_read_b32 v39, v239 offset:6400
	ds_read_b128 v[140:143], v26 offset:9984
	v_mfma_f32_16x16x4_f32 v[244:247], v99, v219, v[244:247]
	ds_read_b128 v[144:147], v26 offset:11008
	ds_read_b128 v[148:151], v26 offset:12032
	ds_read_b128 v[152:155], v26 offset:13056
	v_mfma_f32_16x16x4_f32 v[240:243], v100, v220, v[240:243]
	ds_read_b32 v156, v29 offset:9988
	ds_read_b32 v157, v29 offset:10060
	ds_read_b64 v[158:159], v29 offset:9992
	v_mfma_f32_16x16x4_f32 v[244:247], v101, v221, v[244:247]
	ds_read_b64 v[160:161], v29 offset:10024
	ds_read_b32 v178, v31 offset:9988
	ds_read_b32 v179, v31 offset:10060
	v_mfma_f32_16x16x4_f32 v[240:243], v102, v222, v[240:243]
	ds_read_b64 v[180:181], v31 offset:9992
	ds_read_b64 v[182:183], v31 offset:10024
	ds_read_b64 v[162:163], v30 offset:9984
	v_mfma_f32_16x16x4_f32 v[244:247], v103, v223, v[244:247]
	ds_read_b64 v[164:165], v30 offset:10016
	ds_read_b64 v[166:167], v30 offset:10048
	ds_read_b64 v[168:169], v30 offset:10080
	ds_read_b64 v[170:171], v30 offset:9992
	ds_read_b64 v[172:173], v30 offset:10024
	ds_read_b64 v[174:175], v30 offset:10056
	ds_read_b64 v[176:177], v30 offset:10088
	s_waitcnt lgkmcnt(15)
	v_mfma_f32_16x16x4_f32 v[208:211], v186, v36, v[208:211]
	s_nop 1
	v_pk_add_f32 v[240:241], v[240:241], v[244:245]
	v_pk_add_f32 v[242:243], v[242:243], v[246:247]
	v_fmac_f32_e32 v241, v104, v240
	v_mfma_f32_16x16x4_f32 v[212:215], v190, v36, v[212:215]
	v_pk_fma_f32 v[242:243], v[106:107], v[240:241], v[242:243] op_sel:[0,0,0] op_sel_hi:[1,0,1]
	v_pk_fma_f32 v[242:243], v[108:109], v[240:241], v[242:243] op_sel:[0,1,0] op_sel_hi:[1,1,1]
	v_fmac_f32_e32 v243, v105, v242
	v_mfma_f32_16x16x4_f32 v[216:219], v194, v36, v[216:219]
	ds_bpermute_b32 v204, v232, v240
	ds_bpermute_b32 v205, v232, v241
	ds_bpermute_b32 v206, v232, v242
	v_mfma_f32_16x16x4_f32 v[72:75], v132, v38, 0
	ds_bpermute_b32 v207, v232, v243
	s_waitcnt lgkmcnt(2)
	v_pk_fma_f32 v[240:241], v[110:111], v[204:205], v[240:241] op_sel:[0,0,0] op_sel_hi:[1,0,1]
	v_pk_fma_f32 v[240:241], v[112:113], v[204:205], v[240:241] op_sel:[0,1,0] op_sel_hi:[1,1,1]
	v_mfma_f32_16x16x4_f32 v[72:75], v133, v39, v[72:75]
	s_waitcnt lgkmcnt(0)
	v_pk_fma_f32 v[240:241], v[114:115], v[206:207], v[240:241] op_sel:[0,0,0] op_sel_hi:[1,0,1]
	v_pk_fma_f32 v[240:241], v[116:117], v[206:207], v[240:241] op_sel:[0,1,0] op_sel_hi:[1,1,1]
	v_pk_fma_f32 v[242:243], v[118:119], v[204:205], v[242:243] op_sel:[0,0,0] op_sel_hi:[1,0,1]
	v_mfma_f32_16x16x4_f32 v[220:223], v198, v36, v[220:223]
	v_pk_fma_f32 v[242:243], v[120:121], v[204:205], v[242:243] op_sel:[0,1,0] op_sel_hi:[1,1,1]
	v_pk_fma_f32 v[242:243], v[122:123], v[206:207], v[242:243] op_sel:[0,0,0] op_sel_hi:[1,0,1]
	v_pk_fma_f32 v[242:243], v[124:125], v[206:207], v[242:243] op_sel:[0,1,0] op_sel_hi:[1,1,1]
	v_mfma_f32_16x16x4_f32 v[208:211], v187, v37, v[208:211]
	v_fmac_f32_e32 v241, v126, v240
	v_pk_fma_f32 v[242:243], v[128:129], v[240:241], v[242:243] op_sel:[0,0,0] op_sel_hi:[1,0,1]
	v_pk_fma_f32 v[242:243], v[130:131], v[240:241], v[242:243] op_sel:[0,1,0] op_sel_hi:[1,1,1]
	v_mfma_f32_16x16x4_f32 v[212:215], v191, v37, v[212:215]
	v_fmac_f32_e32 v243, v127, v242
	v_mov_b32_e32 v252, v240
	v_mov_b32_e32 v253, v241
	v_mfma_f32_16x16x4_f32 v[216:219], v195, v37, v[216:219]
	v_mov_b32_e32 v254, v242
	v_mov_b32_e32 v255, v243
	s_nop 0
	v_permlane32_swap_b32_e32 v252, v254
	v_mfma_f32_16x16x4_f32 v[220:223], v199, v37, v[220:223]
	v_permlane32_swap_b32_e32 v253, v255
	v_mfma_f32_16x16x4_f32 v[208:211], v184, v252, v[208:211]
	ds_read_b128 v[88:91], v28
	v_mfma_f32_16x16x4_f32 v[212:215], v188, v252, v[212:215]
	ds_read_b128 v[92:95], v28 offset:64
	v_mfma_f32_16x16x4_f32 v[216:219], v192, v252, v[216:219]
	ds_read_b128 v[96:99], v28 offset:128
	v_mfma_f32_16x16x4_f32 v[220:223], v196, v252, v[220:223]
	ds_read_b128 v[100:103], v28 offset:192
	v_mfma_f32_16x16x4_f32 v[208:211], v185, v253, v[208:211]
	v_mfma_f32_16x16x4_f32 v[212:215], v189, v253, v[212:215]
	v_mfma_f32_16x16x4_f32 v[216:219], v193, v253, v[216:219]
	v_mfma_f32_16x16x4_f32 v[220:223], v197, v253, v[220:223]
	v_mfma_f32_16x16x4_f32 v[248:251], v82, v252, v[240:243]
	v_mfma_f32_16x16x4_f32 v[248:251], v83, v253, v[248:251]
	s_waitcnt lgkmcnt(3)
	v_pk_mul_f32 v[208:209], v[208:209], v[88:89]
	v_pk_mul_f32 v[210:211], v[210:211], v[90:91]
	s_nop 0
	v_mfma_f32_16x16x4_f32 v[72:75], v140, v208, v[72:75]
	s_waitcnt lgkmcnt(2)
	v_pk_mul_f32 v[212:213], v[212:213], v[92:93]
	v_mfma_f32_16x16x4_f32 v[244:247], v141, v209, 0
	v_pk_mul_f32 v[214:215], v[214:215], v[94:95]
	v_mfma_f32_16x16x4_f32 v[72:75], v142, v210, v[72:75]
	s_waitcnt lgkmcnt(1)
	v_pk_mul_f32 v[216:217], v[216:217], v[96:97]
	v_mfma_f32_16x16x4_f32 v[244:247], v143, v211, v[244:247]
	v_pk_mul_f32 v[218:219], v[218:219], v[98:99]
	v_mfma_f32_16x16x4_f32 v[72:75], v144, v212, v[72:75]
	s_waitcnt lgkmcnt(0)
	v_pk_mul_f32 v[220:221], v[220:221], v[100:101]
	v_mfma_f32_16x16x4_f32 v[244:247], v145, v213, v[244:247]
	v_pk_mul_f32 v[222:223], v[222:223], v[102:103]
	v_mfma_f32_16x16x4_f32 v[72:75], v146, v214, v[72:75]
	s_mov_b64 exec, s[98:99]
	ds_write_b32 v231, v248 offset:4096
	ds_write_b32 v231, v249 offset:4352
	ds_write_b32 v231, v250 offset:4608
	ds_write_b32 v231, v251 offset:4864
	s_mov_b64 exec, -1
	ds_read_b64 v[186:187], v35 offset:9984
	ds_read_b64 v[190:191], v35 offset:11008
	v_mfma_f32_16x16x4_f32 v[244:247], v147, v215, v[244:247]
	ds_read_b64 v[194:195], v35 offset:12032
	ds_read_b64 v[198:199], v35 offset:13056
	v_mfma_f32_16x16x4_f32 v[72:75], v148, v216, v[72:75]
	ds_read_b64 v[184:185], v27 offset:9984
	ds_read_b64 v[188:189], v27 offset:11008
	v_mfma_f32_16x16x4_f32 v[244:247], v149, v217, v[244:247]
	ds_read_b64 v[192:193], v27 offset:12032
	ds_read_b64 v[196:197], v27 offset:13056
	v_mfma_f32_16x16x4_f32 v[72:75], v150, v218, v[72:75]
	v_mfma_f32_16x16x4_f32 v[244:247], v151, v219, v[244:247]
	v_mfma_f32_16x16x4_f32 v[72:75], v152, v220, v[72:75]
	v_mfma_f32_16x16x4_f32 v[244:247], v153, v221, v[244:247]
	v_mfma_f32_16x16x4_f32 v[72:75], v154, v222, v[72:75]
	v_mfma_f32_16x16x4_f32 v[244:247], v155, v223, v[244:247]
	s_waitcnt lgkmcnt(7)
	v_mfma_f32_16x16x4_f32 v[208:211], v186, v38, v[208:211]
	s_nop 2
	v_pk_add_f32 v[72:73], v[72:73], v[244:245]
	v_pk_add_f32 v[74:75], v[74:75], v[246:247]
	v_fmac_f32_e32 v73, v156, v72
	s_waitcnt lgkmcnt(6)
	v_mfma_f32_16x16x4_f32 v[212:215], v190, v38, v[212:215]
	v_pk_fma_f32 v[74:75], v[158:159], v[72:73], v[74:75] op_sel:[0,0,0] op_sel_hi:[1,0,1]
	v_pk_fma_f32 v[74:75], v[160:161], v[72:73], v[74:75] op_sel:[0,1,0] op_sel_hi:[1,1,1]
	v_fmac_f32_e32 v75, v157, v74
	s_waitcnt lgkmcnt(5)
	v_mfma_f32_16x16x4_f32 v[216:219], v194, v38, v[216:219]
	ds_bpermute_b32 v204, v232, v72
	ds_bpermute_b32 v205, v232, v73
	ds_bpermute_b32 v206, v232, v74
	s_waitcnt lgkmcnt(7)
	v_mfma_f32_16x16x4_f32 v[220:223], v198, v38, v[220:223]
	ds_bpermute_b32 v207, v232, v75
	s_waitcnt lgkmcnt(2)
	v_pk_fma_f32 v[72:73], v[162:163], v[204:205], v[72:73] op_sel:[0,0,0] op_sel_hi:[1,0,1]
	v_pk_fma_f32 v[72:73], v[164:165], v[204:205], v[72:73] op_sel:[0,1,0] op_sel_hi:[1,1,1]
	v_mfma_f32_16x16x4_f32 v[208:211], v187, v39, v[208:211]
	s_waitcnt lgkmcnt(0)
	v_pk_fma_f32 v[72:73], v[166:167], v[206:207], v[72:73] op_sel:[0,0,0] op_sel_hi:[1,0,1]
	v_pk_fma_f32 v[72:73], v[168:169], v[206:207], v[72:73] op_sel:[0,1,0] op_sel_hi:[1,1,1]
	v_pk_fma_f32 v[74:75], v[170:171], v[204:205], v[74:75] op_sel:[0,0,0] op_sel_hi:[1,0,1]
	v_mfma_f32_16x16x4_f32 v[212:215], v191, v39, v[212:215]
	v_pk_fma_f32 v[74:75], v[172:173], v[204:205], v[74:75] op_sel:[0,1,0] op_sel_hi:[1,1,1]
	v_pk_fma_f32 v[74:75], v[174:175], v[206:207], v[74:75] op_sel:[0,0,0] op_sel_hi:[1,0,1]
	v_pk_fma_f32 v[74:75], v[176:177], v[206:207], v[74:75] op_sel:[0,1,0] op_sel_hi:[1,1,1]
	v_mfma_f32_16x16x4_f32 v[216:219], v195, v39, v[216:219]
	v_fmac_f32_e32 v73, v178, v72
	v_pk_fma_f32 v[74:75], v[180:181], v[72:73], v[74:75] op_sel:[0,0,0] op_sel_hi:[1,0,1]
	v_pk_fma_f32 v[74:75], v[182:183], v[72:73], v[74:75] op_sel:[0,1,0] op_sel_hi:[1,1,1]
	v_mfma_f32_16x16x4_f32 v[220:223], v199, v39, v[220:223]
	v_fmac_f32_e32 v75, v179, v74
	v_mov_b32_e32 v252, v72
	v_mov_b32_e32 v253, v73
	v_mov_b32_e32 v254, v74
	v_mov_b32_e32 v255, v75
	s_nop 0
	v_permlane32_swap_b32_e32 v252, v254
	v_permlane32_swap_b32_e32 v253, v255
	s_nop 0
	v_mfma_f32_16x16x4_f32 v[208:211], v184, v252, v[208:211]
	ds_read_b128 v[140:143], v28 offset:9984
	v_mfma_f32_16x16x4_f32 v[212:215], v188, v252, v[212:215]
	ds_read_b128 v[144:147], v28 offset:10048
	v_mfma_f32_16x16x4_f32 v[216:219], v192, v252, v[216:219]
	ds_read_b128 v[148:151], v28 offset:10112
	v_mfma_f32_16x16x4_f32 v[220:223], v196, v252, v[220:223]
	ds_read_b128 v[152:155], v28 offset:10176
	v_mfma_f32_16x16x4_f32 v[208:211], v185, v253, v[208:211]
	v_mfma_f32_16x16x4_f32 v[212:215], v189, v253, v[212:215]
	v_mfma_f32_16x16x4_f32 v[216:219], v193, v253, v[216:219]
	v_mfma_f32_16x16x4_f32 v[220:223], v197, v253, v[220:223]
	v_mfma_f32_16x16x4_f32 v[248:251], v134, v252, v[72:75]
	v_mfma_f32_16x16x4_f32 v[248:251], v135, v253, v[248:251]
	s_waitcnt lgkmcnt(3)
	v_pk_mul_f32 v[208:209], v[208:209], v[140:141]
	v_pk_mul_f32 v[210:211], v[210:211], v[142:143]
	s_waitcnt lgkmcnt(2)
	v_pk_mul_f32 v[212:213], v[212:213], v[144:145]
	v_pk_mul_f32 v[214:215], v[214:215], v[146:147]
	s_waitcnt lgkmcnt(1)
	v_pk_mul_f32 v[216:217], v[216:217], v[148:149]
	v_pk_mul_f32 v[218:219], v[218:219], v[150:151]
	s_waitcnt lgkmcnt(0)
	v_pk_mul_f32 v[220:221], v[220:221], v[152:153]
	v_pk_mul_f32 v[222:223], v[222:223], v[154:155]
	s_mov_b64 exec, s[98:99]
	s_nop 0
	ds_write_b32 v231, v248 offset:6144
	ds_write_b32 v231, v249 offset:6400
	ds_write_b32 v231, v250 offset:6656
	ds_write_b32 v231, v251 offset:6912
	s_mov_b64 exec, -1
	s_branch .LBB0_655

.Lmy_ck_drE_h:
	s_waitcnt lgkmcnt(0)
	s_bfe_u32 s96, s62, 0x20006
	s_and_b32 s97, s96, 1
	s_mul_i32 s97, s97, 0x2700
	s_mov_b32 s101, 0x1c000
	s_mov_b32 s100, 0x6100
	s_bitcmp0_b32 s65, 0
	s_cselect_b32 s101, 0xe000, s101
	s_cselect_b32 s100, 0x4e00, s100
	s_cmp_gt_u32 s96, 1
	s_cselect_b32 s100, s100, 0
	s_add_i32 s97, s97, s101
	s_add_i32 s97, s97, s100
	s_mov_b32 s96, s97
	v_and_b32_e32 v72, 3, v233
	v_lshrrev_b32_e32 v73, 2, v233
	v_lshlrev_b32_e32 v72, 2, v72
	v_lshl_add_u32 v72, v73, 8, v72
	v_lshl_add_u32 v72, v234, 6, v72
	s_add_i32 s97, s96, 0x1000
	v_add_u32_e32 v78, s97, v72
	v_xor_b32_e32 v79, v224, v234
	v_lshl_add_u32 v79, v79, 4, s96
	ds_read_b128 v[96:99], v79
	ds_read_b128 v[100:103], v79 offset:1024
	ds_read_b128 v[104:107], v79 offset:2048
	ds_read_b128 v[108:111], v79 offset:3072
	ds_read_b32 v80, v78
	ds_read_b32 v81, v78 offset:16
	ds_read_b32 v82, v78 offset:32
	ds_read_b32 v83, v78 offset:48
	ds_read_b32 v84, v78 offset:1024
	ds_read_b32 v85, v78 offset:1040
	ds_read_b32 v86, v78 offset:1056
	ds_read_b32 v87, v78 offset:1072
	ds_read_b32 v88, v78 offset:2048
	ds_read_b32 v89, v78 offset:2064
	ds_read_b32 v90, v78 offset:2080
	ds_read_b32 v91, v78 offset:2096
	ds_read_b32 v92, v78 offset:3072
	ds_read_b32 v93, v78 offset:3088
	ds_read_b32 v94, v78 offset:3104
	ds_read_b32 v95, v78 offset:3120
	v_lshl_add_u32 v74, v224, 2, s96
	ds_write_b32 v74, v235 offset:9728
	v_add_u32_e32 v75, -1, v233
	v_mov_b32_e32 v76, -1
	v_cndmask_b32_e64 v75, v76, v75, s[98:99]
	v_cmp_lt_u32_e64 s[100:101], 7, v233
	v_add_u32_e32 v76, -8, v233
	v_and_b32_e32 v77, 1, v234
	v_cndmask_b32_e64 v75, v75, v76, s[100:101]
	v_lshlrev_b32_e32 v77, 2, v77
	v_sub_u32_e32 v76, v75, v77
	v_lshlrev_b32_e32 v77, 2, v234
	v_sub_u32_e32 v77, v233, v77
	v_add_u32_e32 v77, -1, v77
	s_waitcnt lgkmcnt(15)
	v_mfma_f32_16x16x4_f32 v[244:247], v80, v96, 0
	v_mfma_f32_16x16x4_f32 v[240:243], v81, v97, 0
	s_waitcnt lgkmcnt(14)
	v_mfma_f32_16x16x4_f32 v[244:247], v82, v98, v[244:247]
	s_waitcnt lgkmcnt(13)
	v_mfma_f32_16x16x4_f32 v[240:243], v83, v99, v[240:243]
	s_waitcnt lgkmcnt(12)
	v_mfma_f32_16x16x4_f32 v[244:247], v84, v100, v[244:247]
	s_waitcnt lgkmcnt(11)
	v_mfma_f32_16x16x4_f32 v[240:243], v85, v101, v[240:243]
	s_waitcnt lgkmcnt(10)
	v_mfma_f32_16x16x4_f32 v[244:247], v86, v102, v[244:247]
	s_waitcnt lgkmcnt(9)
	v_mfma_f32_16x16x4_f32 v[240:243], v87, v103, v[240:243]
	s_waitcnt lgkmcnt(8)
	v_mfma_f32_16x16x4_f32 v[244:247], v88, v104, v[244:247]
	s_waitcnt lgkmcnt(7)
	v_mfma_f32_16x16x4_f32 v[240:243], v89, v105, v[240:243]
	s_waitcnt lgkmcnt(6)
	v_mfma_f32_16x16x4_f32 v[244:247], v90, v106, v[244:247]
	s_waitcnt lgkmcnt(5)
	v_mfma_f32_16x16x4_f32 v[240:243], v91, v107, v[240:243]
	s_waitcnt lgkmcnt(4)
	v_mfma_f32_16x16x4_f32 v[244:247], v92, v108, v[244:247]
	s_waitcnt lgkmcnt(3)
	v_mfma_f32_16x16x4_f32 v[240:243], v93, v109, v[240:243]
	s_waitcnt lgkmcnt(2)
	v_mfma_f32_16x16x4_f32 v[244:247], v94, v110, v[244:247]
	s_waitcnt lgkmcnt(1)
	v_mfma_f32_16x16x4_f32 v[240:243], v95, v111, v[240:243]
	s_nop 9
	v_add_f32_e32 v244, v244, v240
	v_add_f32_e32 v245, v245, v241
	v_add_f32_e32 v246, v246, v242
	v_add_f32_e32 v247, v247, v243
	v_cmp_le_i32_e64 s[96:97], 0, v76
	v_cmp_le_i32_e64 s[100:101], 1, v76
	s_nop 0
	v_cndmask_b32_e64 v128, 0, v244, s[96:97]
	v_cndmask_b32_e64 v129, 0, v245, s[100:101]
	v_cmp_le_i32_e64 s[96:97], 2, v76
	v_cmp_le_i32_e64 s[100:101], 3, v76
	s_nop 0
	v_cndmask_b32_e64 v130, 0, v246, s[96:97]
	v_cndmask_b32_e64 v131, 0, v247, s[100:101]
	s_bfe_u32 s96, s62, 0x20006
	s_and_b32 s97, s96, 1
	s_mul_i32 s97, s97, 0x2700
	s_mov_b32 s101, 0x1c000
	s_mov_b32 s100, 0x6100
	s_bitcmp0_b32 s65, 0
	s_cselect_b32 s101, 0xe000, s101
	s_cselect_b32 s100, 0x4e00, s100
	s_cmp_gt_u32 s96, 1
	s_cselect_b32 s100, s100, 0
	s_add_i32 s97, s97, s101
	s_add_i32 s97, s97, s100
	v_xor_b32_e32 v74, v224, v234
	v_lshl_add_u32 v74, v74, 4, s97
	ds_write_b128 v74, v[128:131] offset:8448
	v_lshlrev_b32_e32 v75, 7, v234
	v_lshl_add_u32 v75, v233, 2, v75
	v_add_u32_e32 v75, s97, v75
	v_cmp_le_i32_e64 s[96:97], 0, v77
	v_cmp_le_i32_e64 s[100:101], 1, v77
	s_nop 0
	v_cndmask_b32_e64 v132, 0, v244, s[96:97]
	v_cndmask_b32_e64 v133, 0, v245, s[100:101]
	v_cmp_le_i32_e64 s[96:97], 2, v77
	v_cmp_le_i32_e64 s[100:101], 3, v77
	s_nop 0
	v_cndmask_b32_e64 v134, 0, v246, s[96:97]
	v_cndmask_b32_e64 v135, 0, v247, s[100:101]
	s_mov_b64 exec, 0x00ff00ff
	ds_write_b32 v75, v132 offset:9472
	ds_write_b32 v75, v133 offset:9504
	ds_write_b32 v75, v134 offset:9536
	ds_write_b32 v75, v135 offset:9568
	s_mov_b64 exec, -1
	s_setprio 0
	s_branch .LBB0_655
	s_nop 0
	s_nop 0
	s_nop 0
	s_nop 0
	s_nop 0
	s_nop 0
	s_nop 0
	s_nop 0
	s_nop 0
	s_nop 0
	s_nop 0
	s_nop 0
	s_nop 0
	s_nop 0
	s_nop 0
	s_nop 0
	s_nop 0
	s_nop 0
	s_nop 0
	s_nop 0
	s_nop 0
	s_nop 0
	s_nop 0
	s_nop 0
	s_nop 0
	s_nop 0
	s_nop 0
	s_nop 0
	s_nop 0
	s_nop 0
	s_nop 0
	s_nop 0
	s_nop 0
	s_nop 0
	s_nop 0
	s_nop 0
	s_nop 0
	s_nop 0
	s_nop 0
	s_nop 0
	s_nop 0
	s_nop 0
	s_nop 0
	s_nop 0
	s_nop 0
